# P2 conv: static priority raise for waves 4..7 during the conv part (the two waves of a SIMD drift apart), dropped before memory attention
# baseline (speedup 1.0000x reference)
.LBB0_272:
	s_cmp_lt_i32 s74, 3
	s_cselect_b64 s[2:3], -1, 0
	s_add_u32 s44, s72, 0x5a00000
	s_addc_u32 s45, s73, 0
	s_and_b64 s[2:3], s[2:3], s[0:1]
	s_andn2_b64 vcc, exec, s[2:3]
	s_cbranch_vccnz .LBB0_293
	v_lshlrev_b32_e32 v100, 4, v198
	v_readlane_b32 s4, v254, 40
	v_mov_b32_e32 v101, v100
	global_load_dwordx4 v[104:107], v101, s[62:63]
	v_add_u32_e32 v101, 0x2000, v100
	global_load_dwordx4 v[108:111], v101, s[62:63]
	v_add_u32_e32 v101, 0x4000, v100
	global_load_dwordx4 v[112:115], v101, s[62:63]
	v_add_u32_e32 v101, 0x6000, v100
	global_load_dwordx4 v[116:119], v101, s[62:63]
	v_add_u32_e32 v101, 0x8000, v100
	global_load_dwordx4 v[120:123], v101, s[62:63]
	v_add_u32_e32 v101, 0xa000, v100
	global_load_dwordx4 v[124:127], v101, s[62:63]
	v_add_u32_e32 v101, 0xc000, v100
	global_load_dwordx4 v[128:131], v101, s[62:63]
	v_add_u32_e32 v101, 0xe000, v100
	global_load_dwordx4 v[132:135], v101, s[62:63]
	v_add_u32_e32 v101, 0x10000, v100
	global_load_dwordx4 v[136:139], v101, s[62:63]
	v_add_u32_e32 v101, 0x12000, v100
	global_load_dwordx4 v[140:143], v101, s[62:63]
	v_add_u32_e32 v101, 0x14000, v100
	global_load_dwordx4 v[144:147], v101, s[62:63]
	s_cmp_lt_u32 s4, 4
	s_cbranch_scc1 .Lcv_noprio
	s_setprio 1
.Lcv_noprio:
	s_cmp_lt_u32 s4, 5
	s_cbranch_scc0 .Lcv_pre_skip
	v_add_u32_e32 v101, 0x16000, v100
	global_load_dwordx4 v[148:151], v101, s[62:63]

.LBB0_280:
	s_setprio 0
	v_readlane_b32 s0, v254, 41
	s_cmp_lt_i32 s0, 0
	s_cbranch_scc1 .LBB0_289
	v_readlane_b32 s4, v254, 7
	v_readlane_b32 s12, v254, 15
	v_readlane_b32 s13, v254, 16
	v_readlane_b32 s14, v254, 17
	v_readlane_b32 s15, v254, 18
	v_readlane_b32 s16, v254, 19
	v_readlane_b32 s17, v254, 20
	v_lshlrev_b32_e32 v1, 2, v199
	v_readlane_b32 s18, v254, 21
	v_readlane_b32 s19, v254, 22
	s_mov_b64 s[12:13], s[16:17]
	s_mov_b64 s[14:15], s[18:19]
	global_load_dword v2, v1, s[12:13]
	global_load_dword v3, v1, s[14:15]
	v_mbcnt_lo_u32_b32 v1, -1, 0
	v_mbcnt_hi_u32_b32 v1, -1, v1
	v_and_b32_e32 v4, 64, v1
	v_xor_b32_e32 v5, 1, v1
	v_add_u32_e32 v4, 64, v4
	v_cmp_lt_i32_e32 vcc, v5, v4
	v_xor_b32_e32 v6, 2, v1
	v_xor_b32_e32 v7, 4, v1
	v_cndmask_b32_e32 v5, v1, v5, vcc
	v_lshlrev_b32_e32 v5, 2, v5
	v_cmp_lt_i32_e32 vcc, v6, v4
	v_xor_b32_e32 v8, 8, v1
	v_xor_b32_e32 v9, 16, v1
	v_cndmask_b32_e32 v6, v1, v6, vcc
	v_lshlrev_b32_e32 v6, 2, v6
	v_cmp_lt_i32_e32 vcc, v7, v4
	v_xor_b32_e32 v10, 32, v1
	v_readlane_b32 s0, v254, 41
	v_cndmask_b32_e32 v7, v1, v7, vcc
	v_lshlrev_b32_e32 v7, 2, v7
	v_cmp_lt_i32_e32 vcc, v8, v4
	s_cmpk_gt_u32 s0, 0x7ff
	s_mov_b32 s1, 0
	v_readlane_b32 s5, v254, 8
	v_readlane_b32 s6, v254, 9
	v_readlane_b32 s7, v254, 10
	v_readlane_b32 s8, v254, 11
	v_readlane_b32 s9, v254, 12
	v_readlane_b32 s10, v254, 13
	v_readlane_b32 s11, v254, 14
	s_waitcnt vmcnt(0)
	v_and_b32_e32 v11, 0x7fffffff, v2
	v_and_b32_e32 v12, 0x7fffffff, v3
	ds_bpermute_b32 v11, v5, v11
	ds_bpermute_b32 v5, v5, v12
	v_max_f32_e64 v2, |v2|, |v2|
	v_max_f32_e64 v3, |v3|, |v3|
	s_waitcnt lgkmcnt(1)
	v_max_f32_e32 v11, v11, v11
	s_waitcnt lgkmcnt(0)
	v_max_f32_e32 v5, v5, v5
	v_max_f32_e32 v2, v2, v11
	v_max_f32_e32 v3, v3, v5
	ds_bpermute_b32 v5, v6, v2
	ds_bpermute_b32 v6, v6, v3
	s_waitcnt lgkmcnt(1)
	v_max_f32_e32 v5, v5, v5
	s_waitcnt lgkmcnt(0)
	v_max_f32_e32 v6, v6, v6
	v_max_f32_e32 v2, v2, v5
	v_max_f32_e32 v3, v3, v6
	ds_bpermute_b32 v5, v7, v2
	ds_bpermute_b32 v6, v7, v3
	v_cndmask_b32_e32 v7, v1, v8, vcc
	v_lshlrev_b32_e32 v7, 2, v7
	v_cmp_lt_i32_e32 vcc, v9, v4
	s_waitcnt lgkmcnt(1)
	v_max_f32_e32 v5, v5, v5
	s_waitcnt lgkmcnt(0)
	v_max_f32_e32 v6, v6, v6
	v_max_f32_e32 v2, v2, v5
	v_max_f32_e32 v3, v3, v6
	ds_bpermute_b32 v5, v7, v2
	ds_bpermute_b32 v6, v7, v3
	v_cndmask_b32_e32 v7, v1, v9, vcc
	v_lshlrev_b32_e32 v7, 2, v7
	v_cmp_lt_i32_e32 vcc, v10, v4
	s_waitcnt lgkmcnt(1)
	v_max_f32_e32 v5, v5, v5
	s_waitcnt lgkmcnt(0)
	v_max_f32_e32 v6, v6, v6
	v_max_f32_e32 v2, v2, v5
	v_max_f32_e32 v5, v3, v6
	ds_bpermute_b32 v3, v7, v2
	ds_bpermute_b32 v6, v7, v5
	v_cndmask_b32_e32 v1, v1, v10, vcc
	v_lshlrev_b32_e32 v1, 2, v1
	s_waitcnt lgkmcnt(1)
	v_max_f32_e32 v3, v3, v3
	s_waitcnt lgkmcnt(0)
	v_max_f32_e32 v4, v6, v6
	v_max_f32_e32 v3, v2, v3
	v_max_f32_e32 v2, v5, v4
	ds_bpermute_b32 v5, v1, v3
	ds_bpermute_b32 v4, v1, v2
	s_cbranch_scc1 .LBB0_289
	s_waitcnt lgkmcnt(1)
	v_max_f32_e32 v5, v5, v5
	v_max_f32_e32 v3, v3, v3
	v_readlane_b32 s0, v254, 39
	v_max_f32_e32 v3, v3, v5
	s_waitcnt lgkmcnt(0)
	v_max_f32_e32 v4, v4, v4
	v_max_f32_e32 v2, v2, v2
	s_bfe_u32 s0, s0, 0x20006
	v_mul_f32_e32 v3, 0x4138aa3b, v3
	v_max_f32_e32 v2, v2, v4
	s_lshl_b32 s12, s0, 6
	s_lshl_b32 s4, s0, 7
	v_mul_f32_e32 v2, v3, v2
	s_add_u32 s4, s72, s4
	v_mul_f32_e32 v180, 0x3f828f5c, v2
	v_lshrrev_b32_e32 v3, 5, v199
	v_mov_b32_e32 v2, 0
	s_addc_u32 s5, s73, 0
	s_lshl_b32 s0, s0, 15
	v_lshlrev_b32_e32 v8, 4, v3
	v_mov_b32_e32 v9, v2
	s_add_u32 s0, s72, s0
	v_lshl_add_u64 v[8:9], s[4:5], 0, v[8:9]
	s_mov_b64 s[4:5], 0x9200000
	s_addc_u32 s10, s73, 0
	v_lshl_add_u64 v[164:165], v[8:9], 0, s[4:5]
	s_add_u32 s4, s0, 0x80000
	s_addc_u32 s5, s10, 0
	s_add_u32 s6, s0, 0xc0000
	s_addc_u32 s7, s10, 0
	v_lshlrev_b32_e32 v8, 4, v199
	v_mov_b32_e32 v9, v2
	v_lshl_add_u64 v[166:167], s[4:5], 0, v[8:9]
	v_lshl_add_u64 v[168:169], s[6:7], 0, v[8:9]
	s_mov_b64 s[8:9], 0x1000
	v_lshl_add_u64 v[170:171], v[166:167], 0, s[8:9]
	v_lshl_add_u64 v[172:173], v[168:169], 0, s[8:9]
	s_add_u32 s8, s0, 0x82000
	v_lshlrev_b32_e32 v4, 3, v199
	v_lshlrev_b32_e32 v6, 2, v3
	s_addc_u32 s9, s10, 0
	s_mov_b64 s[10:11], 0x2000
	v_and_b32_e32 v181, 31, v198
	v_lshl_add_u64 v[174:175], v[168:169], 0, s[10:11]
	v_lshlrev_b32_e32 v182, 1, v4
	s_lshl_b32 s0, s12, 1
	v_lshlrev_b32_e32 v176, 1, v6
	s_mov_b64 s[10:11], 0x5a00600
	s_mov_b32 s16, 0x5a00000
	v_readlane_b32 s17, v254, 41
	s_branch .LBB0_284
